# skew 4 WG groups by 2us steps at in-proj GEMM start to de-synchronize epilogue store bursts
# speedup vs baseline: 1.0042x; 1.0042x over previous
.LBB0_124:
	s_lshr_b32 s100, s2, 3
	s_and_b32 s100, s100, 3
.Lskew_loop:
	s_cmp_eq_u32 s100, 0
	s_cbranch_scc1 .Lskew_done
	s_sleep 63
	s_sub_i32 s100, s100, 1
	s_branch .Lskew_loop

	.amdhsa_kernel _Z14fwd_megakernel6Params
		.amdhsa_group_segment_fixed_size 0
		.amdhsa_private_segment_fixed_size 0
		.amdhsa_kernarg_size 448
		.amdhsa_user_sgpr_count 2
		.amdhsa_user_sgpr_dispatch_ptr 0
		.amdhsa_user_sgpr_queue_ptr 0
		.amdhsa_user_sgpr_kernarg_segment_ptr 1
		.amdhsa_user_sgpr_dispatch_id 0
		.amdhsa_user_sgpr_kernarg_preload_length 0
		.amdhsa_user_sgpr_kernarg_preload_offset 0
		.amdhsa_user_sgpr_private_segment_size 0
		.amdhsa_uses_dynamic_stack 0
		.amdhsa_enable_private_segment 0
		.amdhsa_system_sgpr_workgroup_id_x 1
		.amdhsa_system_sgpr_workgroup_id_y 0
		.amdhsa_system_sgpr_workgroup_id_z 0
		.amdhsa_system_sgpr_workgroup_info 0
		.amdhsa_system_vgpr_workitem_id 2
		.amdhsa_next_free_vgpr 256
		.amdhsa_next_free_sgpr 102
		.amdhsa_accum_offset 256
		.amdhsa_reserve_vcc 1
		.amdhsa_float_round_mode_32 0
		.amdhsa_float_round_mode_16_64 0
		.amdhsa_float_denorm_mode_32 3
		.amdhsa_float_denorm_mode_16_64 3
		.amdhsa_dx10_clamp 1
		.amdhsa_ieee_mode 1
		.amdhsa_fp16_overflow 0
		.amdhsa_tg_split 0
		.amdhsa_exception_fp_ieee_invalid_op 0
		.amdhsa_exception_fp_denorm_src 0
		.amdhsa_exception_fp_ieee_div_zero 0
		.amdhsa_exception_fp_ieee_overflow 0
		.amdhsa_exception_fp_ieee_underflow 0
		.amdhsa_exception_fp_ieee_inexact 0
		.amdhsa_exception_int_div_zero 0
	.end_amdhsa_kernel

amdhsa.kernels:
  - .agpr_count:     0
    .args:
      - .offset:         0
        .size:           192
        .value_kind:     by_value
      - .offset:         192
        .size:           4
        .value_kind:     hidden_block_count_x
      - .offset:         196
        .size:           4
        .value_kind:     hidden_block_count_y
      - .offset:         200
        .size:           4
        .value_kind:     hidden_block_count_z
      - .offset:         204
        .size:           2
        .value_kind:     hidden_group_size_x
      - .offset:         206
        .size:           2
        .value_kind:     hidden_group_size_y
      - .offset:         208
        .size:           2
        .value_kind:     hidden_group_size_z
      - .offset:         210
        .size:           2
        .value_kind:     hidden_remainder_x
      - .offset:         212
        .size:           2
        .value_kind:     hidden_remainder_y
      - .offset:         214
        .size:           2
        .value_kind:     hidden_remainder_z
      - .offset:         232
        .size:           8
        .value_kind:     hidden_global_offset_x
      - .offset:         240
        .size:           8
        .value_kind:     hidden_global_offset_y
      - .offset:         248
        .size:           8
        .value_kind:     hidden_global_offset_z
      - .offset:         256
        .size:           2
        .value_kind:     hidden_grid_dims
      - .offset:         280
        .size:           8
        .value_kind:     hidden_multigrid_sync_arg
      - .offset:         312
        .size:           4
        .value_kind:     hidden_dynamic_lds_size
    .group_segment_fixed_size: 0
    .kernarg_segment_align: 8
    .kernarg_segment_size: 448
    .language:       OpenCL C
    .language_version:
      - 2
      - 0
    .max_flat_workgroup_size: 512
    .name:           _Z14fwd_megakernel6Params
    .private_segment_fixed_size: 0
    .sgpr_count:     108
    .sgpr_spill_count: 160
    .symbol:         _Z14fwd_megakernel6Params.kd
    .uniform_work_group_size: 1
    .uses_dynamic_stack: false
    .vgpr_count:     256
    .vgpr_spill_count: 0
    .wavefront_size: 64
